# window/SWA near-tile bias gathers: pairwise deferral (2 reads in flight) where register reuse allows
# baseline (speedup 1.0000x reference)
; template <int MODE, int TM> ...
;     ...
;     const h16* Ks = t ? Ks1 : Ks0;
; #pragma unroll
;     for (int kt = 0; kt < 4; ++kt) {
;       S[t][kt] = f32x4{0.f, 0.f, 0.f, 0.f};
; #pragma unroll
;       for (int ks = 0; ks < 2; ++ks) {
;         h16x8 Kf = *(const h16x8*)(Ks + (kt * 16 + col) * KP + ks * 32 + q4 * 8);
;         S[t][kt] = __builtin_amdgcn_mfma_f32_16x16x32_f16(Kf, Q[ks], S[t][kt], 0, 0, 0);
;       }
;     }
;   }
;   __builtin_amdgcn_s_setprio(0);
;   const float* bt = biasT + hd * 800;
;   float addc[2] = {0.f, 0.f}, sclc[2] = {1.f, 1.f};
; #pragma unroll
;   for (int t = 0; t < 2; ++t) {
;     if (!(TM & (1 << t))) continue;
;     const int kbase = kbase0 + 64 * t;
;     if (far[t]) {
;       const bool ok = (MODE == M_SEL) ? selbit[t] : true;
;       addc[t] = ok ? bt[799] : -1e30f;
;       sclc[t] = SCL2;
;     } else {
;       addc[t] = 0.f;
;       sclc[t] = 1.f;
;       const int kx0 = kbase + q4 * 4;
;       const int d0 = (DK == 16) ? tq - 31 - 16 * kx0 : tq - kx0;
; #pragma unroll
;       for (int kt = 0; kt < 4; ++kt)
; #pragma unroll
;         for (int j = 0; j < 4; ++j) {
;           const int dist = d0 - DK * (kt * 16 + j);
;           const int kx = kx0 + kt * 16 + j;
;           bool valid = dist >= 0;
;           if (MODE == M_WIN) valid = valid && dist < 512 && kx >= 0;
;           if (MODE == M_SEL) valid = valid && selbit[t];
;           if (DK == 16) valid = valid && kx < NCMP;
;           const int dc = dist < 0 ? 0 : (dist > 799 ? 799 : dist);
;           S[t][kt][j] = valid ? S[t][kt][j] * SCL2 + bt[dc] : -1e30f;
;         }
.LBB0_1833:
	s_lshl_b32 s0, s30, 1
	s_add_i32 s2, s0, s20
	s_lshl_b32 s3, s2, 6
	s_cmp_ge_i32 s0, s21
	s_setprio 1
	ds_read_b128 v[112:115], v155 offset:12800
	ds_read_b128 v[108:111], v155 offset:12864
	s_mov_b64 s[0:1], -1
	v_or_b32_e32 v0, s3, v154
	s_cbranch_scc0 .LBB0_1867
	s_waitcnt lgkmcnt(1)
	v_mfma_f32_16x16x32_f16 v[92:95], v[112:115], v[4:7], 0
	ds_read_b128 v[96:99], v155 offset:15360
	ds_read_b128 v[116:119], v155 offset:17920
	s_waitcnt lgkmcnt(2)
	v_mfma_f32_16x16x32_f16 v[104:107], v[108:111], v[8:11], v[92:95]
	s_nop 3
	ds_read_b128 v[92:95], v155 offset:15424
	s_waitcnt lgkmcnt(2)
	v_mfma_f32_16x16x32_f16 v[96:99], v[96:99], v[4:7], 0
	s_waitcnt lgkmcnt(0)
	v_mfma_f32_16x16x32_f16 v[100:103], v[92:95], v[8:11], v[96:99]
	ds_read_b128 v[92:95], v155 offset:17984
	v_mfma_f32_16x16x32_f16 v[96:99], v[116:119], v[4:7], 0
	ds_read_b128 v[116:119], v155 offset:20480
	s_waitcnt lgkmcnt(1)
	v_mfma_f32_16x16x32_f16 v[96:99], v[92:95], v[8:11], v[96:99]
	ds_read_b128 v[92:95], v155 offset:20544
	s_waitcnt lgkmcnt(1)
	v_mfma_f32_16x16x32_f16 v[116:119], v[116:119], v[4:7], 0
	s_waitcnt lgkmcnt(0)
	v_mfma_f32_16x16x32_f16 v[92:95], v[92:95], v[8:11], v[116:119]
	s_setprio 0
	v_sub_u32_e32 v2, v182, v0
	s_cmp_gt_i32 s2, -1
	v_cmp_gt_u32_e32 vcc, s76, v2
	s_cselect_b64 s[0:1], -1, 0
	s_and_b64 s[44:45], s[0:1], vcc
	v_mov_b32_e32 v3, 0xf149f2ca
	v_mov_b32_e32 v116, 0xf149f2ca
	s_and_saveexec_b64 s[0:1], s[44:45]
	s_cbranch_execz .LBB0_1836
	v_lshl_add_u32 v2, v2, 2, v157
	ds_read_b32 v116, v2
.LBB0_1836:
	s_or_b64 exec, exec, s[0:1]
	v_xad_u32 v2, v0, -1, v182
	v_cmp_gt_u32_e32 vcc, s76, v2
	v_cmp_lt_i32_e64 s[0:1], -2, v0
	s_and_b64 s[44:45], s[0:1], vcc
	s_and_saveexec_b64 s[0:1], s[44:45]
	s_cbranch_execz .LBB0_1838
	s_mov_b32 s3, 0x3fffffcc
	v_xad_u32 v2, v0, s3, v182
	v_lshl_add_u32 v2, v2, 2, v157
	ds_read_b32 v3, v2 offset:204
	s_waitcnt lgkmcnt(0)
	v_fmac_f32_e32 v3, 0x3e38aa3b, v105
.LBB0_1838:
	s_or_b64 exec, exec, s[0:1]
	s_waitcnt lgkmcnt(0)
	v_fmac_f32_e32 v116, 0x3e38aa3b, v104
	v_or_b32_e32 v2, 2, v0
	v_sub_u32_e32 v2, v182, v2
	v_cmp_gt_u32_e32 vcc, s76, v2
	v_cmp_lt_i32_e64 s[0:1], -3, v0
	s_and_b64 s[44:45], s[0:1], vcc
	v_mov_b32_e32 v104, 0xf149f2ca
	v_mov_b32_e32 v105, 0xf149f2ca
	s_and_saveexec_b64 s[0:1], s[44:45]
	s_cbranch_execz .LBB0_1840
	v_lshl_add_u32 v2, v2, 2, v157
	ds_read_b32 v105, v2

; template <int MODE, int TM> ...
;     ...
;       const int kx0 = kbase + q4 * 4;
;       const int d0 = (DK == 16) ? tq - 31 - 16 * kx0 : tq - kx0;
; #pragma unroll
;       for (int kt = 0; kt < 4; ++kt)
; #pragma unroll
;         for (int j = 0; j < 4; ++j) {
;           const int dist = d0 - DK * (kt * 16 + j);
;           const int kx = kx0 + kt * 16 + j;
;           bool valid = dist >= 0;
;           if (MODE == M_WIN) valid = valid && dist < 512 && kx >= 0;
;           if (MODE == M_SEL) valid = valid && selbit[t];
;           if (DK == 16) valid = valid && kx < NCMP;
;           const int dc = dist < 0 ? 0 : (dist > 799 ? 799 : dist);
;           S[t][kt][j] = valid ? S[t][kt][j] * SCL2 + bt[dc] : -1e30f;
;         }
.LBB0_1842:
	s_or_b64 exec, exec, s[0:1]
	s_waitcnt lgkmcnt(0)
	v_fmac_f32_e32 v105, 0x3e38aa3b, v106
	v_sub_u32_e32 v2, v228, v0
	s_movk_i32 s0, 0xffef
	v_cmp_gt_u32_e32 vcc, s76, v2
	v_cmp_lt_i32_e64 s[0:1], s0, v0
	s_and_b64 s[44:45], s[0:1], vcc
	v_mov_b32_e32 v106, 0xf149f2ca
	v_mov_b32_e32 v107, 0xf149f2ca
	s_and_saveexec_b64 s[0:1], s[44:45]
	s_cbranch_execz .LBB0_1844
	v_lshl_add_u32 v2, v2, 2, v157
	ds_read_b32 v107, v2

; template <int MODE, int TM> ...
;     ...
;       const int kx0 = kbase + q4 * 4;
;       const int d0 = (DK == 16) ? tq - 31 - 16 * kx0 : tq - kx0;
; #pragma unroll
;       for (int kt = 0; kt < 4; ++kt)
; #pragma unroll
;         for (int j = 0; j < 4; ++j) {
;           const int dist = d0 - DK * (kt * 16 + j);
;           const int kx = kx0 + kt * 16 + j;
;           bool valid = dist >= 0;
;           if (MODE == M_WIN) valid = valid && dist < 512 && kx >= 0;
;           if (MODE == M_SEL) valid = valid && selbit[t];
;           if (DK == 16) valid = valid && kx < NCMP;
;           const int dc = dist < 0 ? 0 : (dist > 799 ? 799 : dist);
;           S[t][kt][j] = valid ? S[t][kt][j] * SCL2 + bt[dc] : -1e30f;
;         }
.LBB0_1846:
	s_or_b64 exec, exec, s[0:1]
	s_waitcnt lgkmcnt(0)
	v_fmac_f32_e32 v107, 0x3e38aa3b, v100
	v_sub_u32_e32 v2, v230, v0
	s_movk_i32 s0, 0xffed
	v_cmp_gt_u32_e32 vcc, s76, v2
	v_cmp_lt_i32_e64 s[0:1], s0, v0
	s_and_b64 s[44:45], s[0:1], vcc
	v_mov_b32_e32 v100, 0xf149f2ca
	v_mov_b32_e32 v101, 0xf149f2ca
	s_and_saveexec_b64 s[0:1], s[44:45]
	s_cbranch_execz .LBB0_1848
	v_lshl_add_u32 v2, v2, 2, v157
	ds_read_b32 v101, v2

; template <int MODE, int TM> ...
;     ...
;       const int kx0 = kbase + q4 * 4;
;       const int d0 = (DK == 16) ? tq - 31 - 16 * kx0 : tq - kx0;
; #pragma unroll
;       for (int kt = 0; kt < 4; ++kt)
; #pragma unroll
;         for (int j = 0; j < 4; ++j) {
;           const int dist = d0 - DK * (kt * 16 + j);
;           const int kx = kx0 + kt * 16 + j;
;           bool valid = dist >= 0;
;           if (MODE == M_WIN) valid = valid && dist < 512 && kx >= 0;
;           if (MODE == M_SEL) valid = valid && selbit[t];
;           if (DK == 16) valid = valid && kx < NCMP;
;           const int dc = dist < 0 ? 0 : (dist > 799 ? 799 : dist);
;           S[t][kt][j] = valid ? S[t][kt][j] * SCL2 + bt[dc] : -1e30f;
;         }
.LBB0_1850:
	s_or_b64 exec, exec, s[0:1]
	s_waitcnt lgkmcnt(0)
	v_fmac_f32_e32 v101, 0x3e38aa3b, v102
	v_sub_u32_e32 v2, v232, v0
	s_movk_i32 s0, 0xffdf
	v_cmp_gt_u32_e32 vcc, s76, v2
	v_cmp_lt_i32_e64 s[0:1], s0, v0
	s_and_b64 s[44:45], s[0:1], vcc
	v_mov_b32_e32 v102, 0xf149f2ca
	v_mov_b32_e32 v103, 0xf149f2ca
	s_and_saveexec_b64 s[0:1], s[44:45]
	s_cbranch_execz .LBB0_1852
	v_lshl_add_u32 v2, v2, 2, v157
	ds_read_b32 v103, v2

; template <int MODE, int TM> ...
;     ...
;       const int kx0 = kbase + q4 * 4;
;       const int d0 = (DK == 16) ? tq - 31 - 16 * kx0 : tq - kx0;
; #pragma unroll
;       for (int kt = 0; kt < 4; ++kt)
; #pragma unroll
;         for (int j = 0; j < 4; ++j) {
;           const int dist = d0 - DK * (kt * 16 + j);
;           const int kx = kx0 + kt * 16 + j;
;           bool valid = dist >= 0;
;           if (MODE == M_WIN) valid = valid && dist < 512 && kx >= 0;
;           if (MODE == M_SEL) valid = valid && selbit[t];
;           if (DK == 16) valid = valid && kx < NCMP;
;           const int dc = dist < 0 ? 0 : (dist > 799 ? 799 : dist);
;           S[t][kt][j] = valid ? S[t][kt][j] * SCL2 + bt[dc] : -1e30f;
;         }
.LBB0_1854:
	s_or_b64 exec, exec, s[0:1]
	s_waitcnt lgkmcnt(0)
	v_fmac_f32_e32 v103, 0x3e38aa3b, v96
	v_sub_u32_e32 v2, v234, v0
	s_movk_i32 s0, 0xffdd
	v_cmp_gt_u32_e32 vcc, s76, v2
	v_cmp_lt_i32_e64 s[0:1], s0, v0
	s_and_b64 s[44:45], s[0:1], vcc
	v_mov_b32_e32 v96, 0xf149f2ca
	v_mov_b32_e32 v97, 0xf149f2ca
	s_and_saveexec_b64 s[0:1], s[44:45]
	s_cbranch_execz .LBB0_1856
	v_lshl_add_u32 v2, v2, 2, v157
	ds_read_b32 v97, v2

; template <int MODE, int TM> ...
;     ...
;       const int kx0 = kbase + q4 * 4;
;       const int d0 = (DK == 16) ? tq - 31 - 16 * kx0 : tq - kx0;
; #pragma unroll
;       for (int kt = 0; kt < 4; ++kt)
; #pragma unroll
;         for (int j = 0; j < 4; ++j) {
;           const int dist = d0 - DK * (kt * 16 + j);
;           const int kx = kx0 + kt * 16 + j;
;           bool valid = dist >= 0;
;           if (MODE == M_WIN) valid = valid && dist < 512 && kx >= 0;
;           if (MODE == M_SEL) valid = valid && selbit[t];
;           if (DK == 16) valid = valid && kx < NCMP;
;           const int dc = dist < 0 ? 0 : (dist > 799 ? 799 : dist);
;           S[t][kt][j] = valid ? S[t][kt][j] * SCL2 + bt[dc] : -1e30f;
;         }
.LBB0_1858:
	s_or_b64 exec, exec, s[0:1]
	s_waitcnt lgkmcnt(0)
	v_fmac_f32_e32 v97, 0x3e38aa3b, v98
	v_sub_u32_e32 v2, v236, v0
	s_movk_i32 s0, 0xffcf
	v_cmp_gt_u32_e32 vcc, s76, v2
	v_cmp_lt_i32_e64 s[0:1], s0, v0
	s_and_b64 s[44:45], s[0:1], vcc
	v_mov_b32_e32 v98, 0xf149f2ca
	v_mov_b32_e32 v99, 0xf149f2ca
	s_and_saveexec_b64 s[0:1], s[44:45]
	s_cbranch_execz .LBB0_1860
	v_lshl_add_u32 v2, v2, 2, v157
	ds_read_b32 v99, v2

; template <int MODE, int TM> ...
;     ...
;       const int kx0 = kbase + q4 * 4;
;       const int d0 = (DK == 16) ? tq - 31 - 16 * kx0 : tq - kx0;
; #pragma unroll
;       for (int kt = 0; kt < 4; ++kt)
; #pragma unroll
;         for (int j = 0; j < 4; ++j) {
;           const int dist = d0 - DK * (kt * 16 + j);
;           const int kx = kx0 + kt * 16 + j;
;           bool valid = dist >= 0;
;           if (MODE == M_WIN) valid = valid && dist < 512 && kx >= 0;
;           if (MODE == M_SEL) valid = valid && selbit[t];
;           if (DK == 16) valid = valid && kx < NCMP;
;           const int dc = dist < 0 ? 0 : (dist > 799 ? 799 : dist);
;           S[t][kt][j] = valid ? S[t][kt][j] * SCL2 + bt[dc] : -1e30f;
;         }
.LBB0_1862:
	s_or_b64 exec, exec, s[0:1]
	s_waitcnt lgkmcnt(0)
	v_fmac_f32_e32 v99, 0x3e38aa3b, v92
	v_sub_u32_e32 v2, v238, v0
	v_cmp_gt_u32_e32 vcc, s76, v2
	v_cmp_lt_i32_e64 s[0:1], s89, v0
	s_and_b64 s[44:45], s[0:1], vcc
	v_mov_b32_e32 v92, 0xf149f2ca
	v_mov_b32_e32 v93, 0xf149f2ca
	s_and_saveexec_b64 s[0:1], s[44:45]
	s_cbranch_execz .LBB0_1864
	v_lshl_add_u32 v2, v2, 2, v157
	ds_read_b32 v93, v2

; #define LAS __attribute__((address_space(3)))
; template <int MODE, int TM> ...
;     ...
;     float mx = -1e30f;
; #pragma unroll
;     for (int t = 0; t < 2; ++t) {
;       if (!(TM & (1 << t))) continue;
;       float mt = -1e30f;
; #pragma unroll
;       for (int kt = 0; kt < 4; ++kt)
; #pragma unroll
;         for (int j = 0; j < 4; ++j) mt = fmaxf(mt, S[t][kt][j]);
;       mx = fmaxf(mx, mt * sclc[t] + addc[t]);
;     }
;     mx = max4q(mx);
;     const float mn = fmaxf(st.m, mx);
;     const float corr = __builtin_amdgcn_exp2f(st.m - mn);
;     st.m = mn;
;     const float mm = fmaxf(mn, -1e20f);
;     float ls = 0.f;
; #pragma unroll
;     for (int t = 0; t < 2; ++t) {
;       if (!(TM & (1 << t))) continue;
;       const float am = addc[t] - mm;
; #pragma unroll
;       for (int kt = 0; kt < 4; ++kt) {
;         const f32x4 e = S[t][kt] * sclc[t] + am;
; #pragma unroll
;         for (int j = 0; j < 4; ++j) {
;           float pv = __builtin_amdgcn_exp2f(e[j]);
;           S[t][kt][j] = pv;
;           ls += pv;
;         }
;       }
;     }
;     st.l = st.l * corr + ls;
;     if (MODE != M_CMPA) {
; #pragma unroll
;       for (int nt = 0; nt < 4; ++nt) O[nt] *= corr;
;     }
;   }
;   if (MODE == M_CMPA) return;
;   __builtin_amdgcn_s_setprio(1);
; #pragma unroll
;   for (int t = 0; t < 2; ++t) {
;     if (!(TM & (1 << t))) continue;
;     const h16* Vt = t ? Vt1 : Vt0;
; #pragma unroll
;     for (int ks = 0; ks < 2; ++ks) {
;       h16x8 Pf;
; #pragma unroll
;       for (int i = 0; i < 4; ++i) { Pf[i] = (h16)S[t][2 * ks][i]; Pf[4 + i] = (h16)S[t][2 * ks + 1][i]; }
; #pragma unroll
;       for (int nt = 0; nt < 4; ++nt) {
;         const h16* vp = Vt + (ks * 32 + q4 * 4 + (col >> 2)) * KP + nt * 16 + 4 * (col & 3);
;         const s16x4v r0 = __builtin_amdgcn_ds_read_tr16_b64_v4i16((LAS s16x4v*)vp);
;         const s16x4v r1 = __builtin_amdgcn_ds_read_tr16_b64_v4i16((LAS s16x4v*)(vp + 16 * KP));
;         const h16x4 v0 = __builtin_bit_cast(h16x4, r0), v1 = __builtin_bit_cast(h16x4, r1);
;         const h16x8 Vf = {v0[0], v0[1], v0[2], v0[3], v1[0], v1[1], v1[2], v1[3]};
;         O[nt] = __builtin_amdgcn_mfma_f32_16x16x32_f16(Vf, Pf, O[nt], 0, 0, 0);
;       }
;     }
;   }
;   __builtin_amdgcn_s_setprio(0);
.LBB0_1866:
	s_or_b64 exec, exec, s[0:1]
	s_waitcnt lgkmcnt(0)
	v_fmac_f32_e32 v93, 0x3e38aa3b, v94
	v_max3_f32 v2, v116, s67, v3
	v_max3_f32 v2, v2, v105, v104
	v_max3_f32 v2, v2, v107, v106
	v_max3_f32 v2, v2, v101, v100
	v_max3_f32 v2, v2, v103, v102
	v_max3_f32 v2, v2, v97, v96
	v_max3_f32 v2, v2, v99, v98
	v_max3_f32 v2, v2, v93, v92
	v_add_f32_e32 v2, 0, v2
	v_max_f32_e32 v2, 0xf149f2ca, v2
	ds_swizzle_b32 v94, v2 offset:swizzle(SWAP,16)
	s_waitcnt lgkmcnt(0)
	v_max_f32_e32 v94, v94, v94
	v_max_f32_e32 v2, v2, v94
	v_mov_b32_e32 v94, v2
	s_nop 1
	v_permlane32_swap_b32_e32 v2, v94
	v_max3_f32 v2, v126, v2, v94
	v_max_f32_e32 v95, 0xe0ad78ec, v2
	v_add_f32_e64 v116, v116, -v95
	v_add_f32_e64 v3, v3, -v95
	v_exp_f32_e32 v116, v116
	v_add_f32_e64 v105, v105, -v95
	v_exp_f32_e32 v120, v3
	v_add_f32_e64 v104, v104, -v95
	v_exp_f32_e32 v117, v105
	v_exp_f32_e32 v121, v104
	v_add_f32_e64 v104, v107, -v95
	v_add_f32_e32 v3, 0, v116
	v_exp_f32_e32 v118, v104
	v_add_f32_e64 v104, v106, -v95
	v_add_f32_e32 v3, v120, v3
	v_exp_f32_e32 v122, v104
	v_add_f32_e64 v101, v101, -v95
	v_add_f32_e32 v3, v117, v3
	v_exp_f32_e32 v119, v101
	v_add_f32_e64 v100, v100, -v95
	v_add_f32_e32 v3, v121, v3
	v_exp_f32_e32 v123, v100
	v_add_f32_e64 v100, v103, -v95
	v_add_f32_e32 v3, v118, v3
	v_exp_f32_e32 v173, v100
	v_add_f32_e64 v100, v102, -v95
	v_add_f32_e32 v3, v122, v3
	v_exp_f32_e32 v188, v100
	v_add_f32_e64 v97, v97, -v95
	v_add_f32_e32 v3, v119, v3
	v_exp_f32_e32 v189, v97
	v_add_f32_e64 v96, v96, -v95
	v_add_f32_e32 v3, v123, v3
	v_exp_f32_e32 v243, v96
	v_add_f32_e64 v96, v99, -v95
	v_add_f32_e32 v3, v173, v3
	v_exp_f32_e32 v248, v96
	v_add_f32_e64 v96, v98, -v95
	v_add_f32_e32 v3, v188, v3
	v_exp_f32_e32 v249, v96
	v_add_f32_e64 v93, v93, -v95
	v_add_f32_e32 v3, v189, v3
	v_exp_f32_e32 v250, v93
	v_add_f32_e64 v92, v92, -v95
	v_sub_f32_e32 v94, v126, v2
	v_add_f32_e32 v3, v243, v3
	v_exp_f32_e32 v251, v92
	v_add_f32_e32 v3, v248, v3
	v_exp_f32_e32 v104, v94
	v_add_f32_e32 v3, v249, v3
	v_add_f32_e32 v3, v250, v3
	v_add_f32_e32 v3, v251, v3
	v_fmac_f32_e32 v3, v127, v104
	v_pk_mul_f32 v[94:95], v[78:79], v[104:105] op_sel_hi:[1,0]
	v_pk_mul_f32 v[92:93], v[76:77], v[104:105] op_sel_hi:[1,0]
	v_pk_mul_f32 v[98:99], v[82:83], v[104:105] op_sel_hi:[1,0]
	v_pk_mul_f32 v[96:97], v[80:81], v[104:105] op_sel_hi:[1,0]
	v_pk_mul_f32 v[102:103], v[86:87], v[104:105] op_sel_hi:[1,0]
	v_pk_mul_f32 v[100:101], v[84:85], v[104:105] op_sel_hi:[1,0]
	v_pk_mul_f32 v[106:107], v[90:91], v[104:105] op_sel_hi:[1,0]
	v_pk_mul_f32 v[104:105], v[88:89], v[104:105] op_sel_hi:[1,0]
	s_setprio 1
	v_cvt_pk_f16_f32 v119, v119, v123
	v_cvt_pk_f16_f32 v118, v118, v122
	v_cvt_pk_f16_f32 v117, v117, v121
	v_cvt_pk_f16_f32 v116, v116, v120
	ds_read_b64_tr_b16 v[122:123], v205 offset:25600
	ds_read_b64_tr_b16 v[120:121], v205 offset:23040
	ds_read_b64_tr_b16 v[244:245], v205 offset:23072
	s_waitcnt lgkmcnt(1)
	v_mfma_f32_16x16x32_f16 v[92:95], v[120:123], v[116:119], v[92:95]
	ds_read_b64_tr_b16 v[246:247], v205 offset:25632
	ds_read_b64_tr_b16 v[120:121], v205 offset:23104
	ds_read_b64_tr_b16 v[122:123], v205 offset:25664
	s_mov_b64 s[0:1], 0
	s_waitcnt lgkmcnt(0)
	v_mfma_f32_16x16x32_f16 v[100:103], v[120:123], v[116:119], v[100:103]
	ds_read_b64_tr_b16 v[120:121], v205 offset:23136
	ds_read_b64_tr_b16 v[122:123], v205 offset:25696
	s_waitcnt lgkmcnt(0)
	v_mfma_f32_16x16x32_f16 v[104:107], v[120:123], v[116:119], v[104:107]
	ds_read_b64_tr_b16 v[120:121], v205 offset:28160
	ds_read_b64_tr_b16 v[122:123], v205 offset:30720
	v_mfma_f32_16x16x32_f16 v[96:99], v[244:247], v[116:119], v[96:99]
	v_cvt_pk_f16_f32 v119, v250, v251
	v_cvt_pk_f16_f32 v118, v248, v249
	v_cvt_pk_f16_f32 v117, v189, v243
	v_cvt_pk_f16_f32 v116, v173, v188
	s_waitcnt lgkmcnt(0)
	s_nop 0
	v_mfma_f32_16x16x32_f16 v[92:95], v[120:123], v[116:119], v[92:95]
	ds_read_b64_tr_b16 v[120:121], v205 offset:28192
	ds_read_b64_tr_b16 v[122:123], v205 offset:30752
	s_waitcnt lgkmcnt(0)
	v_mfma_f32_16x16x32_f16 v[96:99], v[120:123], v[116:119], v[96:99]
	ds_read_b64_tr_b16 v[120:121], v205 offset:28224
	ds_read_b64_tr_b16 v[122:123], v205 offset:30784
	s_waitcnt lgkmcnt(0)
	v_mfma_f32_16x16x32_f16 v[100:103], v[120:123], v[116:119], v[100:103]
	ds_read_b64_tr_b16 v[120:121], v205 offset:28256
	ds_read_b64_tr_b16 v[122:123], v205 offset:30816
	s_waitcnt lgkmcnt(0)
	v_mfma_f32_16x16x32_f16 v[104:107], v[120:123], v[116:119], v[104:107]
; template <int MODE, int TM> ...
;     ...
;     const h16* Ks = t ? Ks1 : Ks0;
; #pragma unroll
;     for (int kt = 0; kt < 4; ++kt) {
;       S[t][kt] = f32x4{0.f, 0.f, 0.f, 0.f};
; #pragma unroll
;       for (int ks = 0; ks < 2; ++ks) {
;         h16x8 Kf = *(const h16x8*)(Ks + (kt * 16 + col) * KP + ks * 32 + q4 * 8);
;         S[t][kt] = __builtin_amdgcn_mfma_f32_16x16x32_f16(Kf, Q[ks], S[t][kt], 0, 0, 0);
;       }
;     }
;   }
;   __builtin_amdgcn_s_setprio(0);
;   const float* bt = biasT + hd * 800;
;   float addc[2] = {0.f, 0.f}, sclc[2] = {1.f, 1.f};
; #pragma unroll
;   for (int t = 0; t < 2; ++t) {
;     if (!(TM & (1 << t))) continue;
;     const int kbase = kbase0 + 64 * t;
;     if (far[t]) {
;       const bool ok = (MODE == M_SEL) ? selbit[t] : true;
;       addc[t] = ok ? bt[799] : -1e30f;
;       sclc[t] = SCL2;
;     } else {
;       addc[t] = 0.f;
;       sclc[t] = 1.f;
;       const int kx0 = kbase + q4 * 4;
;       const int d0 = (DK == 16) ? tq - 31 - 16 * kx0 : tq - kx0;
; #pragma unroll
;       for (int kt = 0; kt < 4; ++kt)
; #pragma unroll
;         for (int j = 0; j < 4; ++j) {
;           const int dist = d0 - DK * (kt * 16 + j);
;           const int kx = kx0 + kt * 16 + j;
;           bool valid = dist >= 0;
;           if (MODE == M_WIN) valid = valid && dist < 512 && kx >= 0;
;           if (MODE == M_SEL) valid = valid && selbit[t];
;           if (DK == 16) valid = valid && kx < NCMP;
;           const int dc = dist < 0 ? 0 : (dist > 799 ? 799 : dist);
;           S[t][kt][j] = valid ? S[t][kt][j] * SCL2 + bt[dc] : -1e30f;
;         }
.LBB0_1867:
	s_and_b64 vcc, exec, s[0:1]
	s_cbranch_vccz .LBB0_1933
	s_waitcnt lgkmcnt(1)
	v_mfma_f32_16x16x32_f16 v[92:95], v[112:115], v[4:7], 0
	ds_read_b128 v[96:99], v155 offset:15360
	ds_read_b128 v[100:103], v155 offset:17920
	ds_read_b128 v[244:247], v155 offset:38400
	s_waitcnt lgkmcnt(3)
	v_mfma_f32_16x16x32_f16 v[120:123], v[108:111], v[8:11], v[92:95]
	s_nop 2
	ds_read_b128 v[92:95], v155 offset:15424
	s_waitcnt lgkmcnt(3)
	v_mfma_f32_16x16x32_f16 v[96:99], v[96:99], v[4:7], 0
	s_waitcnt lgkmcnt(0)
	v_mfma_f32_16x16x32_f16 v[116:119], v[92:95], v[8:11], v[96:99]
	ds_read_b128 v[92:95], v155 offset:17984
	v_mfma_f32_16x16x32_f16 v[96:99], v[100:103], v[4:7], 0
	ds_read_b128 v[100:103], v155 offset:20480
	s_waitcnt lgkmcnt(1)
	v_mfma_f32_16x16x32_f16 v[112:115], v[92:95], v[8:11], v[96:99]
	ds_read_b128 v[92:95], v155 offset:20544
	s_waitcnt lgkmcnt(1)
	v_mfma_f32_16x16x32_f16 v[96:99], v[100:103], v[4:7], 0
	ds_read_b128 v[100:103], v155 offset:33280
	s_waitcnt lgkmcnt(1)
	v_mfma_f32_16x16x32_f16 v[108:111], v[92:95], v[8:11], v[96:99]
	ds_read_b128 v[92:95], v155 offset:33344
	s_waitcnt lgkmcnt(1)
	v_mfma_f32_16x16x32_f16 v[96:99], v[100:103], v[4:7], 0
	ds_read_b128 v[100:103], v155 offset:35840
	s_waitcnt lgkmcnt(1)
	v_mfma_f32_16x16x32_f16 v[104:107], v[92:95], v[8:11], v[96:99]
	ds_read_b128 v[92:95], v155 offset:35904
	s_waitcnt lgkmcnt(1)
	v_mfma_f32_16x16x32_f16 v[96:99], v[100:103], v[4:7], 0
	s_waitcnt lgkmcnt(0)
	v_mfma_f32_16x16x32_f16 v[100:103], v[92:95], v[8:11], v[96:99]
	ds_read_b128 v[92:95], v155 offset:38464
	v_mfma_f32_16x16x32_f16 v[96:99], v[244:247], v[4:7], 0
	ds_read_b128 v[244:247], v155 offset:40960
	s_waitcnt lgkmcnt(1)
	v_mfma_f32_16x16x32_f16 v[96:99], v[92:95], v[8:11], v[96:99]
	ds_read_b128 v[92:95], v155 offset:41024
	s_waitcnt lgkmcnt(1)
	v_mfma_f32_16x16x32_f16 v[244:247], v[244:247], v[4:7], 0
	s_waitcnt lgkmcnt(0)
	v_mfma_f32_16x16x32_f16 v[92:95], v[92:95], v[8:11], v[244:247]
	s_setprio 0
	v_sub_u32_e32 v2, v182, v0
	s_cmp_gt_i32 s2, -1
	v_cmp_gt_u32_e32 vcc, s76, v2
	s_cselect_b64 s[0:1], -1, 0
	s_and_b64 s[2:3], s[0:1], vcc
	v_mov_b32_e32 v3, 0xf149f2ca
	v_mov_b32_e32 v173, 0xf149f2ca
	s_and_saveexec_b64 s[0:1], s[2:3]
	s_cbranch_execz .LBB0_1870
	v_lshl_add_u32 v2, v2, 2, v157
	ds_read_b32 v173, v2
.LBB0_1870:
	s_or_b64 exec, exec, s[0:1]
	v_xad_u32 v2, v0, -1, v182
	v_cmp_gt_u32_e32 vcc, s76, v2
	v_cmp_lt_i32_e64 s[0:1], -2, v0
	s_and_b64 s[2:3], s[0:1], vcc
	s_and_saveexec_b64 s[0:1], s[2:3]
	s_cbranch_execz .LBB0_1872
	s_mov_b32 s2, 0x3fffffcc
	v_xad_u32 v2, v0, s2, v182
	v_lshl_add_u32 v2, v2, 2, v157
	ds_read_b32 v3, v2 offset:204
	s_waitcnt lgkmcnt(0)
	v_fmac_f32_e32 v3, 0x3e38aa3b, v121
.LBB0_1872:
	s_or_b64 exec, exec, s[0:1]
	s_waitcnt lgkmcnt(0)
	v_fmac_f32_e32 v173, 0x3e38aa3b, v120
	v_or_b32_e32 v2, 2, v0
	v_sub_u32_e32 v2, v182, v2
	v_cmp_gt_u32_e32 vcc, s76, v2
	v_cmp_lt_i32_e64 s[0:1], -3, v0
	s_and_b64 s[2:3], s[0:1], vcc
	v_mov_b32_e32 v120, 0xf149f2ca
	v_mov_b32_e32 v121, 0xf149f2ca
	s_and_saveexec_b64 s[0:1], s[2:3]
	s_cbranch_execz .LBB0_1874
	v_lshl_add_u32 v2, v2, 2, v157
	ds_read_b32 v121, v2

; template <int MODE, int TM> ...
;     ...
;       const int kx0 = kbase + q4 * 4;
;       const int d0 = (DK == 16) ? tq - 31 - 16 * kx0 : tq - kx0;
; #pragma unroll
;       for (int kt = 0; kt < 4; ++kt)
; #pragma unroll
;         for (int j = 0; j < 4; ++j) {
;           const int dist = d0 - DK * (kt * 16 + j);
;           const int kx = kx0 + kt * 16 + j;
;           bool valid = dist >= 0;
;           if (MODE == M_WIN) valid = valid && dist < 512 && kx >= 0;
;           if (MODE == M_SEL) valid = valid && selbit[t];
;           if (DK == 16) valid = valid && kx < NCMP;
;           const int dc = dist < 0 ? 0 : (dist > 799 ? 799 : dist);
;           S[t][kt][j] = valid ? S[t][kt][j] * SCL2 + bt[dc] : -1e30f;
;         }
.LBB0_1876:
	s_or_b64 exec, exec, s[0:1]
	s_waitcnt lgkmcnt(0)
	v_fmac_f32_e32 v121, 0x3e38aa3b, v122
	v_sub_u32_e32 v2, v228, v0
	s_movk_i32 s0, 0xffef
	v_cmp_gt_u32_e32 vcc, s76, v2
	v_cmp_lt_i32_e64 s[0:1], s0, v0
	s_and_b64 s[2:3], s[0:1], vcc
	v_mov_b32_e32 v122, 0xf149f2ca
	v_mov_b32_e32 v123, 0xf149f2ca
	s_and_saveexec_b64 s[0:1], s[2:3]
	s_cbranch_execz .LBB0_1878
	v_lshl_add_u32 v2, v2, 2, v157
	ds_read_b32 v123, v2

; template <int MODE, int TM> ...
;     ...
;       const int kx0 = kbase + q4 * 4;
;       const int d0 = (DK == 16) ? tq - 31 - 16 * kx0 : tq - kx0;
; #pragma unroll
;       for (int kt = 0; kt < 4; ++kt)
; #pragma unroll
;         for (int j = 0; j < 4; ++j) {
;           const int dist = d0 - DK * (kt * 16 + j);
;           const int kx = kx0 + kt * 16 + j;
;           bool valid = dist >= 0;
;           if (MODE == M_WIN) valid = valid && dist < 512 && kx >= 0;
;           if (MODE == M_SEL) valid = valid && selbit[t];
;           if (DK == 16) valid = valid && kx < NCMP;
;           const int dc = dist < 0 ? 0 : (dist > 799 ? 799 : dist);
;           S[t][kt][j] = valid ? S[t][kt][j] * SCL2 + bt[dc] : -1e30f;
;         }
.LBB0_1880:
	s_or_b64 exec, exec, s[0:1]
	s_waitcnt lgkmcnt(0)
	v_fmac_f32_e32 v123, 0x3e38aa3b, v116
	v_sub_u32_e32 v2, v230, v0
	s_movk_i32 s0, 0xffed
	v_cmp_gt_u32_e32 vcc, s76, v2
	v_cmp_lt_i32_e64 s[0:1], s0, v0
	s_and_b64 s[2:3], s[0:1], vcc
	v_mov_b32_e32 v116, 0xf149f2ca
	v_mov_b32_e32 v117, 0xf149f2ca
	s_and_saveexec_b64 s[0:1], s[2:3]
	s_cbranch_execz .LBB0_1882
	v_lshl_add_u32 v2, v2, 2, v157
	ds_read_b32 v117, v2

; template <int MODE, int TM> ...
;     ...
;       const int kx0 = kbase + q4 * 4;
;       const int d0 = (DK == 16) ? tq - 31 - 16 * kx0 : tq - kx0;
; #pragma unroll
;       for (int kt = 0; kt < 4; ++kt)
; #pragma unroll
;         for (int j = 0; j < 4; ++j) {
;           const int dist = d0 - DK * (kt * 16 + j);
;           const int kx = kx0 + kt * 16 + j;
;           bool valid = dist >= 0;
;           if (MODE == M_WIN) valid = valid && dist < 512 && kx >= 0;
;           if (MODE == M_SEL) valid = valid && selbit[t];
;           if (DK == 16) valid = valid && kx < NCMP;
;           const int dc = dist < 0 ? 0 : (dist > 799 ? 799 : dist);
;           S[t][kt][j] = valid ? S[t][kt][j] * SCL2 + bt[dc] : -1e30f;
;         }
.LBB0_1884:
	s_or_b64 exec, exec, s[0:1]
	s_waitcnt lgkmcnt(0)
	v_fmac_f32_e32 v117, 0x3e38aa3b, v118
	v_sub_u32_e32 v2, v232, v0
	s_movk_i32 s0, 0xffdf
	v_cmp_gt_u32_e32 vcc, s76, v2
	v_cmp_lt_i32_e64 s[0:1], s0, v0
	s_and_b64 s[2:3], s[0:1], vcc
	v_mov_b32_e32 v118, 0xf149f2ca
	v_mov_b32_e32 v119, 0xf149f2ca
	s_and_saveexec_b64 s[0:1], s[2:3]
	s_cbranch_execz .LBB0_1886
	v_lshl_add_u32 v2, v2, 2, v157
	ds_read_b32 v119, v2

; template <int MODE, int TM> ...
;     ...
;       const int kx0 = kbase + q4 * 4;
;       const int d0 = (DK == 16) ? tq - 31 - 16 * kx0 : tq - kx0;
; #pragma unroll
;       for (int kt = 0; kt < 4; ++kt)
; #pragma unroll
;         for (int j = 0; j < 4; ++j) {
;           const int dist = d0 - DK * (kt * 16 + j);
;           const int kx = kx0 + kt * 16 + j;
;           bool valid = dist >= 0;
;           if (MODE == M_WIN) valid = valid && dist < 512 && kx >= 0;
;           if (MODE == M_SEL) valid = valid && selbit[t];
;           if (DK == 16) valid = valid && kx < NCMP;
;           const int dc = dist < 0 ? 0 : (dist > 799 ? 799 : dist);
;           S[t][kt][j] = valid ? S[t][kt][j] * SCL2 + bt[dc] : -1e30f;
;         }
.LBB0_1888:
	s_or_b64 exec, exec, s[0:1]
	s_waitcnt lgkmcnt(0)
	v_fmac_f32_e32 v119, 0x3e38aa3b, v112
	v_sub_u32_e32 v2, v234, v0
	s_movk_i32 s0, 0xffdd
	v_cmp_gt_u32_e32 vcc, s76, v2
	v_cmp_lt_i32_e64 s[0:1], s0, v0
	s_and_b64 s[2:3], s[0:1], vcc
	v_mov_b32_e32 v112, 0xf149f2ca
	v_mov_b32_e32 v113, 0xf149f2ca
	s_and_saveexec_b64 s[0:1], s[2:3]
	s_cbranch_execz .LBB0_1890
	v_lshl_add_u32 v2, v2, 2, v157
	ds_read_b32 v113, v2

; template <int MODE, int TM> ...
;     ...
;       const int kx0 = kbase + q4 * 4;
;       const int d0 = (DK == 16) ? tq - 31 - 16 * kx0 : tq - kx0;
; #pragma unroll
;       for (int kt = 0; kt < 4; ++kt)
; #pragma unroll
;         for (int j = 0; j < 4; ++j) {
;           const int dist = d0 - DK * (kt * 16 + j);
;           const int kx = kx0 + kt * 16 + j;
;           bool valid = dist >= 0;
;           if (MODE == M_WIN) valid = valid && dist < 512 && kx >= 0;
;           if (MODE == M_SEL) valid = valid && selbit[t];
;           if (DK == 16) valid = valid && kx < NCMP;
;           const int dc = dist < 0 ? 0 : (dist > 799 ? 799 : dist);
;           S[t][kt][j] = valid ? S[t][kt][j] * SCL2 + bt[dc] : -1e30f;
;         }
.LBB0_1892:
	s_or_b64 exec, exec, s[0:1]
	s_waitcnt lgkmcnt(0)
	v_fmac_f32_e32 v113, 0x3e38aa3b, v114
	v_sub_u32_e32 v2, v236, v0
	s_movk_i32 s0, 0xffcf
	v_cmp_gt_u32_e32 vcc, s76, v2
	v_cmp_lt_i32_e64 s[0:1], s0, v0
	s_and_b64 s[2:3], s[0:1], vcc
	v_mov_b32_e32 v114, 0xf149f2ca
	v_mov_b32_e32 v115, 0xf149f2ca
	s_and_saveexec_b64 s[0:1], s[2:3]
	s_cbranch_execz .LBB0_1894
	v_lshl_add_u32 v2, v2, 2, v157
	ds_read_b32 v115, v2

; template <int MODE, int TM> ...
;     ...
;       const int kx0 = kbase + q4 * 4;
;       const int d0 = (DK == 16) ? tq - 31 - 16 * kx0 : tq - kx0;
; #pragma unroll
;       for (int kt = 0; kt < 4; ++kt)
; #pragma unroll
;         for (int j = 0; j < 4; ++j) {
;           const int dist = d0 - DK * (kt * 16 + j);
;           const int kx = kx0 + kt * 16 + j;
;           bool valid = dist >= 0;
;           if (MODE == M_WIN) valid = valid && dist < 512 && kx >= 0;
;           if (MODE == M_SEL) valid = valid && selbit[t];
;           if (DK == 16) valid = valid && kx < NCMP;
;           const int dc = dist < 0 ? 0 : (dist > 799 ? 799 : dist);
;           S[t][kt][j] = valid ? S[t][kt][j] * SCL2 + bt[dc] : -1e30f;
;         }
.LBB0_1896:
	s_or_b64 exec, exec, s[0:1]
	s_waitcnt lgkmcnt(0)
	v_fmac_f32_e32 v115, 0x3e38aa3b, v108
	v_sub_u32_e32 v2, v238, v0
	v_cmp_gt_u32_e32 vcc, s76, v2
	v_cmp_lt_i32_e64 s[0:1], s89, v0
	s_and_b64 s[2:3], s[0:1], vcc
	v_mov_b32_e32 v108, 0xf149f2ca
	v_mov_b32_e32 v109, 0xf149f2ca
	s_and_saveexec_b64 s[0:1], s[2:3]
	s_cbranch_execz .LBB0_1898
	v_lshl_add_u32 v2, v2, 2, v157
	ds_read_b32 v109, v2

; template <int MODE, int TM> ...
;     ...
;       const int kx0 = kbase + q4 * 4;
;       const int d0 = (DK == 16) ? tq - 31 - 16 * kx0 : tq - kx0;
; #pragma unroll
;       for (int kt = 0; kt < 4; ++kt)
; #pragma unroll
;         for (int j = 0; j < 4; ++j) {
;           const int dist = d0 - DK * (kt * 16 + j);
;           const int kx = kx0 + kt * 16 + j;
;           bool valid = dist >= 0;
;           if (MODE == M_WIN) valid = valid && dist < 512 && kx >= 0;
;           if (MODE == M_SEL) valid = valid && selbit[t];
;           if (DK == 16) valid = valid && kx < NCMP;
;           const int dc = dist < 0 ? 0 : (dist > 799 ? 799 : dist);
;           S[t][kt][j] = valid ? S[t][kt][j] * SCL2 + bt[dc] : -1e30f;
;         }
.LBB0_1900:
	s_or_b64 exec, exec, s[0:1]
	s_waitcnt lgkmcnt(0)
	v_fmac_f32_e32 v109, 0x3e38aa3b, v110
	v_sub_u32_e32 v2, 0xffffffbf, v0
	v_sub_u32_e32 v188, v175, v0
	v_cmp_gt_u32_e32 vcc, s76, v188
	v_cmp_gt_i32_e64 s[0:1], 0, v2
	s_and_b64 s[2:3], vcc, s[0:1]
	v_mov_b32_e32 v110, 0xf149f2ca
	v_mov_b32_e32 v111, 0xf149f2ca
	s_and_saveexec_b64 s[0:1], s[2:3]
	s_cbranch_execz .LBB0_1902
	v_lshl_add_u32 v111, v188, 2, v157
	ds_read_b32 v111, v111
	s_waitcnt lgkmcnt(0)
	v_fmac_f32_e32 v111, 0x3e38aa3b, v104

; template <int MODE, int TM> ...
;     ...
;       const int kx0 = kbase + q4 * 4;
;       const int d0 = (DK == 16) ? tq - 31 - 16 * kx0 : tq - kx0;
; #pragma unroll
;       for (int kt = 0; kt < 4; ++kt)
; #pragma unroll
;         for (int j = 0; j < 4; ++j) {
;           const int dist = d0 - DK * (kt * 16 + j);
;           const int kx = kx0 + kt * 16 + j;
;           bool valid = dist >= 0;
;           if (MODE == M_WIN) valid = valid && dist < 512 && kx >= 0;
;           if (MODE == M_SEL) valid = valid && selbit[t];
;           if (DK == 16) valid = valid && kx < NCMP;
;           const int dc = dist < 0 ? 0 : (dist > 799 ? 799 : dist);
;           S[t][kt][j] = valid ? S[t][kt][j] * SCL2 + bt[dc] : -1e30f;
;         }
;     }
;   }
;   if (MODE == M_CMPB) {
; #pragma unroll
;     for (int t = 0; t < 2; ++t) {
;       if (!(TM & (1 << t))) continue;
; #pragma unroll
;       for (int kt = 0; kt < 4; ++kt) {
;         float h = 0.f;
; #pragma unroll
;         for (int j = 0; j < 4; ++j) {
;           float pv = __builtin_amdgcn_exp2f(S[t][kt][j] * sclc[t] + (addc[t] - st.m)) * st.l;
;           S[t][kt][j] = pv;
;           h += pv;
;         }
;         hq[t][kt] = h;
;         h3[t][kt] = S[t][kt][3];
;       }
;     }
;   } else {
;     float mx = -1e30f;
; #pragma unroll
;     for (int t = 0; t < 2; ++t) {
;       if (!(TM & (1 << t))) continue;
;       float mt = -1e30f;
; #pragma unroll
;       for (int kt = 0; kt < 4; ++kt)
; #pragma unroll
;         for (int j = 0; j < 4; ++j) mt = fmaxf(mt, S[t][kt][j]);
;       mx = fmaxf(mx, mt * sclc[t] + addc[t]);
;     }
;     mx = max4q(mx);
;     const float mn = fmaxf(st.m, mx);
;     const float corr = __builtin_amdgcn_exp2f(st.m - mn);
;     st.m = mn;
;     const float mm = fmaxf(mn, -1e20f);
;     float ls = 0.f;
; #pragma unroll
;     for (int t = 0; t < 2; ++t) {
;       if (!(TM & (1 << t))) continue;
;       const float am = addc[t] - mm;
; #pragma unroll
;       for (int kt = 0; kt < 4; ++kt) {
;         const f32x4 e = S[t][kt] * sclc[t] + am;
; #pragma unroll
;         for (int j = 0; j < 4; ++j) {
;           float pv = __builtin_amdgcn_exp2f(e[j]);
;           S[t][kt][j] = pv;
;           ls += pv;
;         }
;       }
;     }
;     st.l = st.l * corr + ls;
;     if (MODE != M_CMPA) {
; #pragma unroll
;       for (int nt = 0; nt < 4; ++nt) O[nt] *= corr;
;     }
;   }
.LBB0_1928:
	s_or_b64 exec, exec, s[0:1]
	v_sub_u32_e32 v188, v226, v0
	v_cmp_gt_u32_e32 vcc, s76, v188
	v_cmp_gt_i32_e64 s[0:1], 2, v2
	s_and_b64 s[2:3], vcc, s[0:1]
	v_mov_b32_e32 v92, 0xf149f2ca
	v_mov_b32_e32 v93, 0xf149f2ca
	s_and_saveexec_b64 s[0:1], s[2:3]
	s_cbranch_execz .LBB0_1930
	v_lshl_add_u32 v93, v188, 2, v157
	ds_read_b32 v93, v93
.LBB0_1930:
	s_or_b64 exec, exec, s[0:1]
	v_sub_u32_e32 v0, v227, v0
	v_cmp_gt_u32_e32 vcc, s76, v0
	v_cmp_gt_i32_e64 s[0:1], 3, v2
	s_and_b64 s[2:3], vcc, s[0:1]
	s_and_saveexec_b64 s[0:1], s[2:3]
	s_cbranch_execz .LBB0_1932
	v_lshl_add_u32 v0, v0, 2, v157
	ds_read_b32 v92, v0
	s_waitcnt lgkmcnt(0)
	v_fmac_f32_e32 v92, 0x3e38aa3b, v95
.LBB0_1932:
	s_or_b64 exec, exec, s[0:1]
	s_waitcnt lgkmcnt(0)
	v_fmac_f32_e32 v93, 0x3e38aa3b, v94
	v_max3_f32 v0, v173, s67, v3
	v_max3_f32 v2, v111, s67, v110
	v_max3_f32 v0, v0, v121, v120
	v_max3_f32 v2, v2, v105, v104
	v_max3_f32 v0, v0, v123, v122
	v_max3_f32 v2, v2, v107, v106
	v_max3_f32 v0, v0, v117, v116
	v_max3_f32 v2, v2, v101, v100
	v_max3_f32 v0, v0, v119, v118
	v_max3_f32 v2, v2, v103, v102
	v_max3_f32 v0, v0, v113, v112
	v_max3_f32 v2, v2, v97, v96
	v_max3_f32 v0, v0, v115, v114
	v_max3_f32 v2, v2, v99, v98
	v_max3_f32 v0, v0, v109, v108
	v_max3_f32 v2, v2, v93, v92
	v_add_f32_e32 v0, 0, v0
	v_add_f32_e32 v2, 0, v2
	v_max3_f32 v0, v0, s67, v2
	ds_swizzle_b32 v2, v0 offset:swizzle(SWAP,16)
	s_waitcnt lgkmcnt(0)
	v_max_f32_e32 v2, v2, v2
	v_max_f32_e32 v0, v0, v2
	v_mov_b32_e32 v2, v0
	s_nop 1
	v_permlane32_swap_b32_e32 v0, v2
	v_max3_f32 v2, v126, v0, v2
	v_max_f32_e32 v0, 0xe0ad78ec, v2
	v_add_f32_e64 v94, v173, -v0
	v_exp_f32_e32 v173, v94
	v_add_f32_e64 v3, v3, -v0
	v_sub_f32_e32 v94, v126, v2
	v_exp_f32_e32 v126, v3
	v_add_f32_e64 v3, v121, -v0
	v_exp_f32_e32 v121, v3
	v_add_f32_e64 v3, v120, -v0
	v_add_f32_e32 v95, 0, v173
	v_exp_f32_e32 v120, v3
	v_add_f32_e64 v3, v123, -v0
	v_exp_f32_e32 v123, v3
	v_add_f32_e32 v3, v126, v95
	v_add_f32_e64 v95, v122, -v0
	v_exp_f32_e32 v122, v95
	v_add_f32_e64 v95, v117, -v0
	v_add_f32_e32 v3, v121, v3
	v_exp_f32_e32 v95, v95
	v_add_f32_e64 v116, v116, -v0
	v_add_f32_e32 v3, v120, v3
	v_exp_f32_e32 v116, v116
	v_add_f32_e64 v117, v119, -v0
	v_add_f32_e32 v3, v123, v3
	v_exp_f32_e32 v117, v117
	v_add_f32_e64 v118, v118, -v0
	v_add_f32_e32 v3, v122, v3
	v_exp_f32_e32 v118, v118
	v_add_f32_e64 v113, v113, -v0
	v_add_f32_e32 v3, v95, v3
	v_exp_f32_e32 v113, v113
	v_add_f32_e64 v112, v112, -v0
	v_add_f32_e32 v3, v116, v3
	v_exp_f32_e32 v112, v112
	v_add_f32_e64 v115, v115, -v0
	v_add_f32_e32 v3, v117, v3
	v_exp_f32_e32 v115, v115
	v_add_f32_e64 v114, v114, -v0
	v_add_f32_e32 v3, v118, v3
	v_exp_f32_e32 v114, v114
	v_add_f32_e64 v109, v109, -v0
	v_add_f32_e32 v3, v113, v3
	v_exp_f32_e32 v109, v109
	v_add_f32_e64 v108, v108, -v0
	v_add_f32_e32 v3, v112, v3
	v_exp_f32_e32 v108, v108
	v_add_f32_e64 v111, v111, -v0
	v_add_f32_e32 v3, v115, v3
	v_exp_f32_e32 v111, v111
	v_add_f32_e64 v110, v110, -v0
	v_add_f32_e32 v3, v114, v3
	v_exp_f32_e32 v110, v110
	v_add_f32_e64 v105, v105, -v0
	v_add_f32_e32 v3, v109, v3
	v_exp_f32_e32 v105, v105
	v_add_f32_e64 v104, v104, -v0
	v_add_f32_e32 v3, v108, v3
	v_exp_f32_e32 v104, v104
	v_add_f32_e64 v107, v107, -v0
	v_add_f32_e32 v3, v111, v3
	v_exp_f32_e32 v107, v107
	v_add_f32_e64 v106, v106, -v0
	v_add_f32_e32 v3, v110, v3
	v_exp_f32_e32 v106, v106
	v_add_f32_e64 v101, v101, -v0
	v_add_f32_e32 v3, v105, v3
	v_exp_f32_e32 v119, v101
	v_add_f32_e64 v100, v100, -v0
	v_add_f32_e32 v3, v104, v3
	v_exp_f32_e32 v188, v100
	v_add_f32_e64 v100, v103, -v0
	v_add_f32_e32 v3, v107, v3
	v_exp_f32_e32 v189, v100
	v_add_f32_e64 v100, v102, -v0
	v_add_f32_e32 v3, v106, v3
	v_exp_f32_e32 v243, v100
	v_add_f32_e64 v97, v97, -v0
	v_add_f32_e32 v3, v119, v3
	v_exp_f32_e32 v244, v97
	v_add_f32_e64 v96, v96, -v0
	v_add_f32_e32 v3, v188, v3
	v_exp_f32_e32 v245, v96
	v_add_f32_e64 v96, v99, -v0
	v_add_f32_e32 v3, v189, v3
	v_exp_f32_e32 v246, v96
	v_add_f32_e64 v96, v98, -v0
	v_add_f32_e32 v3, v243, v3
	v_exp_f32_e32 v247, v96
	v_add_f32_e64 v93, v93, -v0
	v_add_f32_e32 v3, v244, v3
	v_exp_f32_e32 v248, v93
	v_add_f32_e64 v0, v92, -v0
	v_add_f32_e32 v3, v245, v3
	v_exp_f32_e32 v249, v0
	v_add_f32_e32 v3, v246, v3
	v_exp_f32_e32 v0, v94
	v_add_f32_e32 v3, v247, v3
	v_add_f32_e32 v3, v248, v3
	v_add_f32_e32 v3, v249, v3
	v_fmac_f32_e32 v3, v127, v0
	v_pk_mul_f32 v[78:79], v[78:79], v[0:1] op_sel_hi:[1,0]
	v_pk_mul_f32 v[76:77], v[76:77], v[0:1] op_sel_hi:[1,0]
	v_pk_mul_f32 v[82:83], v[82:83], v[0:1] op_sel_hi:[1,0]
	v_pk_mul_f32 v[80:81], v[80:81], v[0:1] op_sel_hi:[1,0]
	v_pk_mul_f32 v[86:87], v[86:87], v[0:1] op_sel_hi:[1,0]
	v_pk_mul_f32 v[84:85], v[84:85], v[0:1] op_sel_hi:[1,0]
	v_pk_mul_f32 v[90:91], v[90:91], v[0:1] op_sel_hi:[1,0]
	v_pk_mul_f32 v[88:89], v[88:89], v[0:1] op_sel_hi:[1,0]
	s_setprio 1
	ds_read_b64_tr_b16 v[98:99], v205 offset:25600
	ds_read_b64_tr_b16 v[96:97], v205 offset:23040
	ds_read_b64_tr_b16 v[100:101], v205 offset:23072
	v_cvt_pk_f16_f32 v95, v95, v116
	v_cvt_pk_f16_f32 v94, v123, v122
	v_cvt_pk_f16_f32 v93, v121, v120
	v_cvt_pk_f16_f32 v92, v173, v126
	ds_read_b64_tr_b16 v[102:103], v205 offset:25632
	s_waitcnt lgkmcnt(2)
; #define LAS __attribute__((address_space(3)))
; template <int MODE, int TM> ...
;     ...
;   __builtin_amdgcn_s_setprio(1);
; #pragma unroll
;   for (int t = 0; t < 2; ++t) {
;     if (!(TM & (1 << t))) continue;
;     const h16* Vt = t ? Vt1 : Vt0;
; #pragma unroll
;     for (int ks = 0; ks < 2; ++ks) {
;       h16x8 Pf;
; #pragma unroll
;       for (int i = 0; i < 4; ++i) { Pf[i] = (h16)S[t][2 * ks][i]; Pf[4 + i] = (h16)S[t][2 * ks + 1][i]; }
; #pragma unroll
;       for (int nt = 0; nt < 4; ++nt) {
;         const h16* vp = Vt + (ks * 32 + q4 * 4 + (col >> 2)) * KP + nt * 16 + 4 * (col & 3);
;         const s16x4v r0 = __builtin_amdgcn_ds_read_tr16_b64_v4i16((LAS s16x4v*)vp);
;         const s16x4v r1 = __builtin_amdgcn_ds_read_tr16_b64_v4i16((LAS s16x4v*)(vp + 16 * KP));
;         const h16x4 v0 = __builtin_bit_cast(h16x4, r0), v1 = __builtin_bit_cast(h16x4, r1);
;         const h16x8 Vf = {v0[0], v0[1], v0[2], v0[3], v1[0], v1[1], v1[2], v1[3]};
;         O[nt] = __builtin_amdgcn_mfma_f32_16x16x32_f16(Vf, Pf, O[nt], 0, 0, 0);
;       }
;     }
;   }
;   __builtin_amdgcn_s_setprio(0);
	v_mfma_f32_16x16x32_f16 v[76:79], v[96:99], v[92:95], v[76:79]
	ds_read_b64_tr_b16 v[96:97], v205 offset:23104
	ds_read_b64_tr_b16 v[98:99], v205 offset:25664
	s_waitcnt lgkmcnt(0)
	v_mfma_f32_16x16x32_f16 v[84:87], v[96:99], v[92:95], v[84:87]
	ds_read_b64_tr_b16 v[96:97], v205 offset:23136
	ds_read_b64_tr_b16 v[98:99], v205 offset:25696
	s_waitcnt lgkmcnt(0)
	v_mfma_f32_16x16x32_f16 v[88:91], v[96:99], v[92:95], v[88:91]
	ds_read_b64_tr_b16 v[96:97], v205 offset:28160
	ds_read_b64_tr_b16 v[98:99], v205 offset:30720
	v_mfma_f32_16x16x32_f16 v[80:83], v[100:103], v[92:95], v[80:83]
	v_cvt_pk_f16_f32 v95, v109, v108
	v_cvt_pk_f16_f32 v94, v115, v114
	v_cvt_pk_f16_f32 v93, v113, v112
	v_cvt_pk_f16_f32 v92, v117, v118
	s_waitcnt lgkmcnt(0)
	s_nop 0
	v_mfma_f32_16x16x32_f16 v[76:79], v[96:99], v[92:95], v[76:79]
	ds_read_b64_tr_b16 v[96:97], v205 offset:28192
	ds_read_b64_tr_b16 v[98:99], v205 offset:30752
	s_waitcnt lgkmcnt(0)
	v_mfma_f32_16x16x32_f16 v[80:83], v[96:99], v[92:95], v[80:83]
	ds_read_b64_tr_b16 v[96:97], v205 offset:28224
	ds_read_b64_tr_b16 v[98:99], v205 offset:30784
	s_waitcnt lgkmcnt(0)
	v_mfma_f32_16x16x32_f16 v[84:87], v[96:99], v[92:95], v[84:87]
	ds_read_b64_tr_b16 v[96:97], v205 offset:28256
	ds_read_b64_tr_b16 v[98:99], v205 offset:30816
	s_waitcnt lgkmcnt(0)
	v_mfma_f32_16x16x32_f16 v[88:91], v[96:99], v[92:95], v[88:91]
	ds_read_b64_tr_b16 v[96:97], v205 offset:43520
	ds_read_b64_tr_b16 v[98:99], v205 offset:46080
	v_cvt_pk_f16_f32 v95, v119, v188
	v_cvt_pk_f16_f32 v94, v107, v106
	v_cvt_pk_f16_f32 v93, v105, v104
	v_cvt_pk_f16_f32 v92, v111, v110
	v_cvt_pk_f16_f32 v107, v248, v249
	v_cvt_pk_f16_f32 v106, v246, v247
	s_waitcnt lgkmcnt(0)
	v_mfma_f32_16x16x32_f16 v[76:79], v[96:99], v[92:95], v[76:79]
	ds_read_b64_tr_b16 v[96:97], v205 offset:43552
	ds_read_b64_tr_b16 v[98:99], v205 offset:46112
	v_cvt_pk_f16_f32 v105, v244, v245
	v_cvt_pk_f16_f32 v104, v189, v243
	s_waitcnt lgkmcnt(0)
	v_mfma_f32_16x16x32_f16 v[80:83], v[96:99], v[92:95], v[80:83]
	ds_read_b64_tr_b16 v[96:97], v205 offset:43584
	ds_read_b64_tr_b16 v[98:99], v205 offset:46144
	s_waitcnt lgkmcnt(0)
	v_mfma_f32_16x16x32_f16 v[84:87], v[96:99], v[92:95], v[84:87]
	ds_read_b64_tr_b16 v[96:97], v205 offset:43616
	ds_read_b64_tr_b16 v[98:99], v205 offset:46176
	s_waitcnt lgkmcnt(0)
	v_mfma_f32_16x16x32_f16 v[88:91], v[96:99], v[92:95], v[88:91]
	ds_read_b64_tr_b16 v[92:93], v205 offset:48640
	ds_read_b64_tr_b16 v[94:95], v205 offset:51200
	s_waitcnt lgkmcnt(0)
	v_mfma_f32_16x16x32_f16 v[92:95], v[92:95], v[104:107], v[76:79]
	s_nop 2
	ds_read_b64_tr_b16 v[76:77], v205 offset:48672
	ds_read_b64_tr_b16 v[78:79], v205 offset:51232
	s_waitcnt lgkmcnt(0)
	v_mfma_f32_16x16x32_f16 v[96:99], v[76:79], v[104:107], v[80:83]
	ds_read_b64_tr_b16 v[76:77], v205 offset:48704
	ds_read_b64_tr_b16 v[78:79], v205 offset:51264
	s_waitcnt lgkmcnt(0)
	v_mfma_f32_16x16x32_f16 v[100:103], v[76:79], v[104:107], v[84:87]
	ds_read_b64_tr_b16 v[76:77], v205 offset:48736
	ds_read_b64_tr_b16 v[78:79], v205 offset:51296
	s_waitcnt lgkmcnt(0)
	v_mfma_f32_16x16x32_f16 v[104:107], v[76:79], v[104:107], v[88:91]

; template <int MODE, int RGM> ...
;     ...
;       const int kx0 = kbase + q4 * 4;
;       const int d0 = (DK == 16) ? tq[rg] - 31 - 16 * kx0 : tq[rg] - kx0;
; #pragma unroll
;       for (int kt = 0; kt < 4; ++kt)
; #pragma unroll
;         for (int j = 0; j < 4; ++j) {
;           const int dist = d0 - DK * (kt * 16 + j);
;           const int kx = kx0 + kt * 16 + j;
;           bool valid = dist >= 0;
;           if (MODE == M_SWA) valid = valid && dist < 128 && kx >= 0;
;           if (MODE == M_WIN) valid = valid && dist < 512 && kx >= 0;
;           if (MODE == M_SEL) valid = valid && selbit[rg];
;           if (DK == 16) valid = valid && kx < NCMP;
;           const int dc = dist < 0 ? 0 : (dist > 799 ? 799 : dist);
;           S[rg][kt][j] = valid ? S[rg][kt][j] * SCL2 + bt[dc] : -1e30f;
.LBB0_2172:
	s_or_b64 exec, exec, s[0:1]
	v_add_u32_e32 v82, 0x4f, v132
	v_cmp_gt_u32_e64 s[0:1], s77, v82
	v_cmp_lt_i32_e64 s[54:55], s73, v133
	s_and_b64 s[56:57], s[54:55], s[0:1]
	s_and_saveexec_b64 s[0:1], s[56:57]
	s_cbranch_execz .LBB0_2174
	ds_read_b32 v88, v131 offset:316
.LBB0_2174:
	s_or_b64 exec, exec, s[0:1]
	v_add_u32_e32 v82, 0x4e, v132
	v_cmp_gt_u32_e64 s[0:1], s77, v82
	v_cmp_lt_i32_e64 s[56:57], s89, v133
	s_and_b64 s[58:59], s[56:57], s[0:1]
	v_mov_b32_e32 v134, 0xf149f2ca
	v_mov_b32_e32 v135, 0xf149f2ca
	s_and_saveexec_b64 s[0:1], s[58:59]
	s_cbranch_execz .LBB0_2176
	ds_read_b32 v135, v131 offset:312
	s_waitcnt lgkmcnt(0)
	v_fmac_f32_e32 v135, 0x3e38aa3b, v84
.LBB0_2176:
	s_or_b64 exec, exec, s[0:1]
	s_waitcnt lgkmcnt(0)
	v_fmac_f32_e32 v88, 0x3e38aa3b, v83
	v_add_u32_e32 v82, 0x4d, v132
	v_cmp_gt_u32_e64 s[0:1], s77, v82
	v_cmp_lt_i32_e64 s[58:59], s33, v133
	s_and_b64 s[74:75], s[58:59], s[0:1]
	s_and_saveexec_b64 s[0:1], s[74:75]
	s_cbranch_execz .LBB0_2178
	ds_read_b32 v134, v131 offset:308
	s_waitcnt lgkmcnt(0)
	v_fmac_f32_e32 v134, 0x3e38aa3b, v85

; template <int MODE, int RGM> ...
;     ...
;       const int kx0 = kbase + q4 * 4;
;       const int d0 = (DK == 16) ? tq[rg] - 31 - 16 * kx0 : tq[rg] - kx0;
; #pragma unroll
;       for (int kt = 0; kt < 4; ++kt)
; #pragma unroll
;         for (int j = 0; j < 4; ++j) {
;           const int dist = d0 - DK * (kt * 16 + j);
;           const int kx = kx0 + kt * 16 + j;
;           bool valid = dist >= 0;
;           if (MODE == M_SWA) valid = valid && dist < 128 && kx >= 0;
;           if (MODE == M_WIN) valid = valid && dist < 512 && kx >= 0;
;           if (MODE == M_SEL) valid = valid && selbit[rg];
;           if (DK == 16) valid = valid && kx < NCMP;
;           const int dc = dist < 0 ? 0 : (dist > 799 ? 799 : dist);
;           S[rg][kt][j] = valid ? S[rg][kt][j] * SCL2 + bt[dc] : -1e30f;
.LBB0_2180:
	s_or_b64 exec, exec, s[0:1]
	v_add_u32_e32 v78, 0x8f, v132
	v_cmp_gt_u32_e64 s[0:1], s77, v78
	s_and_b64 s[28:29], s[28:29], s[0:1]
	s_and_saveexec_b64 s[0:1], s[28:29]
	s_cbranch_execz .LBB0_2182
	ds_read_b32 v82, v131 offset:572
.LBB0_2182:
	s_or_b64 exec, exec, s[0:1]
	v_add_u32_e32 v78, 0x8e, v132
	v_cmp_gt_u32_e64 s[0:1], s77, v78
	s_and_b64 s[28:29], s[30:31], s[0:1]
	v_mov_b32_e32 v84, 0xf149f2ca
	v_mov_b32_e32 v85, 0xf149f2ca
	s_and_saveexec_b64 s[0:1], s[28:29]
	s_cbranch_execz .LBB0_2184
	ds_read_b32 v85, v131 offset:568
	s_waitcnt lgkmcnt(0)
	v_fmac_f32_e32 v85, 0x3e38aa3b, v80
.LBB0_2184:
	s_or_b64 exec, exec, s[0:1]
	s_waitcnt lgkmcnt(0)
	v_fmac_f32_e32 v82, 0x3e38aa3b, v79
	v_add_u32_e32 v78, 0x8d, v132
	v_cmp_gt_u32_e64 s[0:1], s77, v78
	s_and_b64 s[28:29], s[34:35], s[0:1]
	s_and_saveexec_b64 s[0:1], s[28:29]
	s_cbranch_execz .LBB0_2186
	ds_read_b32 v84, v131 offset:564

; template <int MODE, int RGM> ...
;     ...
;       const int kx0 = kbase + q4 * 4;
;       const int d0 = (DK == 16) ? tq[rg] - 31 - 16 * kx0 : tq[rg] - kx0;
; #pragma unroll
;       for (int kt = 0; kt < 4; ++kt)
; #pragma unroll
;         for (int j = 0; j < 4; ++j) {
;           const int dist = d0 - DK * (kt * 16 + j);
;           const int kx = kx0 + kt * 16 + j;
;           bool valid = dist >= 0;
;           if (MODE == M_SWA) valid = valid && dist < 128 && kx >= 0;
;           if (MODE == M_WIN) valid = valid && dist < 512 && kx >= 0;
;           if (MODE == M_SEL) valid = valid && selbit[rg];
;           if (DK == 16) valid = valid && kx < NCMP;
;           const int dc = dist < 0 ? 0 : (dist > 799 ? 799 : dist);
;           S[rg][kt][j] = valid ? S[rg][kt][j] * SCL2 + bt[dc] : -1e30f;
.LBB0_2188:
	s_or_b64 exec, exec, s[0:1]
	s_waitcnt lgkmcnt(0)
	v_fmac_f32_e32 v84, 0x3e38aa3b, v81
	s_and_b64 s[6:7], s[38:39], s[6:7]
	s_and_saveexec_b64 s[0:1], s[6:7]
	s_cbranch_execz .LBB0_2190
	ds_read_b32 v132, v131 offset:508

; template <int MODE, int RGM> ...
;     ...
;       const int kx0 = kbase + q4 * 4;
;       const int d0 = (DK == 16) ? tq[rg] - 31 - 16 * kx0 : tq[rg] - kx0;
; #pragma unroll
;       for (int kt = 0; kt < 4; ++kt)
; #pragma unroll
;         for (int j = 0; j < 4; ++j) {
;           const int dist = d0 - DK * (kt * 16 + j);
;           const int kx = kx0 + kt * 16 + j;
;           bool valid = dist >= 0;
;           if (MODE == M_SWA) valid = valid && dist < 128 && kx >= 0;
;           if (MODE == M_WIN) valid = valid && dist < 512 && kx >= 0;
;           if (MODE == M_SEL) valid = valid && selbit[rg];
;           if (DK == 16) valid = valid && kx < NCMP;
;           const int dc = dist < 0 ? 0 : (dist > 799 ? 799 : dist);
;           S[rg][kt][j] = valid ? S[rg][kt][j] * SCL2 + bt[dc] : -1e30f;
.LBB0_2192:
	s_or_b64 exec, exec, s[0:1]
	s_waitcnt lgkmcnt(0)
	v_fmac_f32_e32 v132, 0x3e38aa3b, v75
	s_and_b64 s[6:7], s[42:43], s[10:11]
	s_and_saveexec_b64 s[0:1], s[6:7]
	s_cbranch_execz .LBB0_2194
	ds_read_b32 v74, v131 offset:500

; template <int MODE, int RGM> ...
;     ...
;       const int kx0 = kbase + q4 * 4;
;       const int d0 = (DK == 16) ? tq[rg] - 31 - 16 * kx0 : tq[rg] - kx0;
; #pragma unroll
;       for (int kt = 0; kt < 4; ++kt)
; #pragma unroll
;         for (int j = 0; j < 4; ++j) {
;           const int dist = d0 - DK * (kt * 16 + j);
;           const int kx = kx0 + kt * 16 + j;
;           bool valid = dist >= 0;
;           if (MODE == M_SWA) valid = valid && dist < 128 && kx >= 0;
;           if (MODE == M_WIN) valid = valid && dist < 512 && kx >= 0;
;           if (MODE == M_SEL) valid = valid && selbit[rg];
;           if (DK == 16) valid = valid && kx < NCMP;
;           const int dc = dist < 0 ? 0 : (dist > 799 ? 799 : dist);
;           S[rg][kt][j] = valid ? S[rg][kt][j] * SCL2 + bt[dc] : -1e30f;
.LBB0_2196:
	s_or_b64 exec, exec, s[0:1]
	s_waitcnt lgkmcnt(0)
	v_fmac_f32_e32 v74, 0x3e38aa3b, v77
	s_and_b64 s[6:7], s[46:47], s[14:15]
	s_and_saveexec_b64 s[0:1], s[6:7]
	s_cbranch_execz .LBB0_2198
	ds_read_b32 v137, v131 offset:444

; template <int MODE, int RGM> ...
;     ...
;       const int kx0 = kbase + q4 * 4;
;       const int d0 = (DK == 16) ? tq[rg] - 31 - 16 * kx0 : tq[rg] - kx0;
; #pragma unroll
;       for (int kt = 0; kt < 4; ++kt)
; #pragma unroll
;         for (int j = 0; j < 4; ++j) {
;           const int dist = d0 - DK * (kt * 16 + j);
;           const int kx = kx0 + kt * 16 + j;
;           bool valid = dist >= 0;
;           if (MODE == M_SWA) valid = valid && dist < 128 && kx >= 0;
;           if (MODE == M_WIN) valid = valid && dist < 512 && kx >= 0;
;           if (MODE == M_SEL) valid = valid && selbit[rg];
;           if (DK == 16) valid = valid && kx < NCMP;
;           const int dc = dist < 0 ? 0 : (dist > 799 ? 799 : dist);
;           S[rg][kt][j] = valid ? S[rg][kt][j] * SCL2 + bt[dc] : -1e30f;
.LBB0_2200:
	s_or_b64 exec, exec, s[0:1]
	s_waitcnt lgkmcnt(0)
	v_fmac_f32_e32 v137, 0x3e38aa3b, v71
	s_and_b64 s[6:7], s[50:51], s[18:19]
	s_and_saveexec_b64 s[0:1], s[6:7]
	s_cbranch_execz .LBB0_2202
	ds_read_b32 v139, v131 offset:436

; template <int MODE, int RGM> ...
;     ...
;       const int kx0 = kbase + q4 * 4;
;       const int d0 = (DK == 16) ? tq[rg] - 31 - 16 * kx0 : tq[rg] - kx0;
; #pragma unroll
;       for (int kt = 0; kt < 4; ++kt)
; #pragma unroll
;         for (int j = 0; j < 4; ++j) {
;           const int dist = d0 - DK * (kt * 16 + j);
;           const int kx = kx0 + kt * 16 + j;
;           bool valid = dist >= 0;
;           if (MODE == M_SWA) valid = valid && dist < 128 && kx >= 0;
;           if (MODE == M_WIN) valid = valid && dist < 512 && kx >= 0;
;           if (MODE == M_SEL) valid = valid && selbit[rg];
;           if (DK == 16) valid = valid && kx < NCMP;
;           const int dc = dist < 0 ? 0 : (dist > 799 ? 799 : dist);
;           S[rg][kt][j] = valid ? S[rg][kt][j] * SCL2 + bt[dc] : -1e30f;
.LBB0_2204:
	s_or_b64 exec, exec, s[0:1]
	s_waitcnt lgkmcnt(0)
	v_fmac_f32_e32 v139, 0x3e38aa3b, v73
	s_and_b64 s[6:7], s[54:55], s[22:23]
	s_and_saveexec_b64 s[0:1], s[6:7]
	s_cbranch_execz .LBB0_2206
	ds_read_b32 v80, v131 offset:380

; template <int MODE, int RGM> ...
;     ...
;       const int kx0 = kbase + q4 * 4;
;       const int d0 = (DK == 16) ? tq[rg] - 31 - 16 * kx0 : tq[rg] - kx0;
; #pragma unroll
;       for (int kt = 0; kt < 4; ++kt)
; #pragma unroll
;         for (int j = 0; j < 4; ++j) {
;           const int dist = d0 - DK * (kt * 16 + j);
;           const int kx = kx0 + kt * 16 + j;
;           bool valid = dist >= 0;
;           if (MODE == M_SWA) valid = valid && dist < 128 && kx >= 0;
;           if (MODE == M_WIN) valid = valid && dist < 512 && kx >= 0;
;           if (MODE == M_SEL) valid = valid && selbit[rg];
;           if (DK == 16) valid = valid && kx < NCMP;
;           const int dc = dist < 0 ? 0 : (dist > 799 ? 799 : dist);
;           S[rg][kt][j] = valid ? S[rg][kt][j] * SCL2 + bt[dc] : -1e30f;
.LBB0_2208:
	s_or_b64 exec, exec, s[0:1]
	s_waitcnt lgkmcnt(0)
	v_fmac_f32_e32 v80, 0x3e38aa3b, v67
	s_and_b64 s[6:7], s[58:59], s[26:27]
	s_and_saveexec_b64 s[0:1], s[6:7]
	s_cbranch_execz .LBB0_2210
	ds_read_b32 v78, v131 offset:372
	s_waitcnt lgkmcnt(0)
	v_fmac_f32_e32 v78, 0x3e38aa3b, v69
